# lever 1 counted waits, complete form: uniform state-wave memory-op streams with exact vmcnt (32-kk / 13 / 22) on top of the pair-split touch
# baseline (speedup 1.0000x reference)
.Lpf_even_p3:
	s_and_b64 vcc, exec, s[16:17]
	s_cbranch_vccz .Lpf_isdw_p3
	v_readfirstlane_b32 s98, v236
	v_readfirstlane_b32 s99, v237
	v_readfirstlane_b32 s100, v238
	s_nop 3
	v_mov_b32_e32 v236, s98
	v_mov_b32_e32 v237, s99
	v_mov_b32_e32 v238, s100
	v_mov_b32_e32 v242, 0
.Lpf_isdw_p3:
	s_waitcnt vmcnt(0)
	s_branch .LBB0_252

.LBB0_252:
	s_min_u32 s75, s74, 0x7d
	s_add_i32 s75, s75, 2
	s_lshl_b32 s26, s75, 6
	s_add_i32 s26, s26, s94
	v_mad_i64_i32 v[4:5], s[26:27], s26, v230, v[146:147]
	s_waitcnt vmcnt(22)
	v_add_co_u32_e32 v82, vcc, s81, v4
	s_waitcnt lgkmcnt(0)
	s_barrier
	s_nop 0
	v_addc_co_u32_e32 v83, vcc, 0, v5, vcc
	global_load_dwordx4 v[142:145], v[4:5], off
	global_load_dwordx4 v[138:141], v[82:83], off offset:256
	v_add_co_u32_e32 v82, vcc, s82, v4
	s_nop 1
	v_addc_co_u32_e32 v83, vcc, 0, v5, vcc
	v_add_co_u32_e32 v84, vcc, s83, v4
	s_nop 1
	v_addc_co_u32_e32 v85, vcc, 0, v5, vcc
	global_load_dwordx4 v[126:129], v[82:83], off offset:512
	global_load_dwordx4 v[122:125], v[84:85], off offset:768
	v_add_co_u32_e32 v82, vcc, s84, v4
	s_nop 1
	v_addc_co_u32_e32 v83, vcc, 0, v5, vcc
	v_add_co_u32_e32 v84, vcc, 0x3c000, v4
	s_nop 1
	v_addc_co_u32_e32 v85, vcc, 0, v5, vcc
	global_load_dwordx4 v[94:97], v[82:83], off offset:1024
	global_load_dwordx4 v[90:93], v[84:85], off offset:1280
	v_add_co_u32_e32 v82, vcc, 0x48000, v4
	s_nop 1
	v_addc_co_u32_e32 v83, vcc, 0, v5, vcc
	v_add_co_u32_e32 v4, vcc, 0x54000, v4
	s_nop 1
	v_addc_co_u32_e32 v5, vcc, 0, v5, vcc
	global_load_dwordx4 v[86:89], v[82:83], off offset:1536
	s_nop 0
	global_load_dwordx4 v[82:85], v[4:5], off offset:1792
	s_and_b64 vcc, exec, s[16:17]
	s_lshl_b32 s26, s75, 2
	s_add_i32 s26, s26, s22
	s_ashr_i32 s27, s26, 31
	s_lshl_b64 s[26:27], s[26:27], 10
	v_lshl_add_u64 v[4:5], v[158:159], 0, s[26:27]
	global_load_dwordx4 v[78:81], v[4:5], off
	s_min_u32 s99, s74, 0x7d
	s_add_i32 s99, s99, 4
	s_min_u32 s99, s99, 0x7f
	v_mad_u64_u32 v[240:241], vcc, v238, s99, v[236:237]
	global_load_dword v239, v[240:241], off
	s_lshl_b32 s99, s99, 6
	s_add_i32 s99, s99, s94
	s_mul_hi_u32 s101, s99, 0x6080
	s_mul_i32 s100, s99, 0x6080
	s_add_u32 s100, s100, s56
	s_addc_u32 s101, s101, s57
	global_load_dword v239, v242, s[100:101]
.LBB0_254:
	s_and_b32 s95, s74, 1
	s_lshl_b32 s27, s95, 10
	s_mul_i32 s26, s95, 0x1200
	s_add_i32 s86, s27, 0
	v_add_u32_e32 v2, s26, v206
	s_add_i32 s26, s23, s86
	v_add_u32_e32 v5, v2, v208
	v_lshl_add_u32 v2, v205, 2, s26
	ds_read_b128 v[168:171], v2 offset:43008
	ds_read_b128 v[172:175], v5 offset:33792
	ds_read_b128 v[176:179], v5 offset:33856
	ds_read_b128 v[180:183], v5 offset:36096
	ds_read_b128 v[184:187], v5 offset:36160
	s_xor_b32 s96, s95, 1
	s_waitcnt lgkmcnt(4)
	v_pk_mul_f32 v[116:117], v[116:117], v[170:171]
	v_pk_mul_f32 v[114:115], v[114:115], v[168:169]
	v_pk_mul_f32 v[112:113], v[112:113], v[170:171]
	v_pk_mul_f32 v[110:111], v[110:111], v[168:169]
	s_waitcnt vmcnt(32) lgkmcnt(3)
	v_mfma_f32_16x16x32_bf16 v[114:117], v[50:53], v[172:175], v[114:117]
	s_mul_i32 s26, s96, 0x4200
	v_add_u32_e32 v4, s26, v165
	v_add_u32_e32 v4, v4, v209
	s_waitcnt lgkmcnt(1)
	v_mfma_f32_16x16x32_bf16 v[50:53], v[50:53], v[180:183], v[110:113]
	s_and_b64 vcc, exec, s[16:17]
	s_lshl_b32 s75, s96, 10
	s_waitcnt vmcnt(31)
	v_mfma_f32_16x16x32_bf16 v[114:117], v[54:57], v[176:179], v[114:117]
	s_waitcnt lgkmcnt(0)
	v_mfma_f32_16x16x32_bf16 v[110:113], v[54:57], v[184:187], v[50:53]
	s_nop 5
	v_cvt_pk_bf16_f32 v232, v114, v115
	v_cvt_pk_bf16_f32 v233, v116, v117
	v_cvt_pk_bf16_f32 v50, v110, v111
	v_cvt_pk_bf16_f32 v51, v112, v113
	ds_write_b64 v4, v[232:233]
	ds_write_b64 v4, v[50:51] offset:8448
	ds_read_b128 v[50:53], v2 offset:43072
	s_waitcnt lgkmcnt(0)
	v_pk_mul_f32 v[56:57], v[120:121], v[52:53]
	v_pk_mul_f32 v[54:55], v[118:119], v[50:51]
	v_pk_mul_f32 v[52:53], v[108:109], v[52:53]
	v_pk_mul_f32 v[50:51], v[106:107], v[50:51]
	s_waitcnt vmcnt(30)
	v_mfma_f32_16x16x32_bf16 v[54:57], v[38:41], v[172:175], v[54:57]
	v_mfma_f32_16x16x32_bf16 v[38:41], v[38:41], v[180:183], v[50:53]
	s_waitcnt vmcnt(29)
	v_mfma_f32_16x16x32_bf16 v[118:121], v[42:45], v[176:179], v[54:57]
	v_mfma_f32_16x16x32_bf16 v[106:109], v[42:45], v[184:187], v[38:41]
	s_nop 6
	v_cvt_pk_bf16_f32 v50, v118, v119
	v_cvt_pk_bf16_f32 v51, v120, v121
	v_cvt_pk_bf16_f32 v38, v106, v107
	v_cvt_pk_bf16_f32 v39, v108, v109
	ds_write_b64 v4, v[50:51] offset:32
	ds_write_b64 v4, v[38:39] offset:8480
	ds_read_b128 v[38:41], v2 offset:43136
	s_waitcnt lgkmcnt(0)
	v_pk_mul_f32 v[44:45], v[136:137], v[40:41]
	v_pk_mul_f32 v[42:43], v[134:135], v[38:39]
	v_pk_mul_f32 v[40:41], v[104:105], v[40:41]
	v_pk_mul_f32 v[38:39], v[102:103], v[38:39]
	s_waitcnt vmcnt(28)
	v_mfma_f32_16x16x32_bf16 v[42:45], v[26:29], v[172:175], v[42:45]
	v_mfma_f32_16x16x32_bf16 v[26:29], v[26:29], v[180:183], v[38:41]
	s_waitcnt vmcnt(27)
	v_mfma_f32_16x16x32_bf16 v[134:137], v[30:33], v[176:179], v[42:45]
	v_mfma_f32_16x16x32_bf16 v[102:105], v[30:33], v[184:187], v[26:29]
	s_nop 6
	v_cvt_pk_bf16_f32 v38, v134, v135
	v_cvt_pk_bf16_f32 v39, v136, v137
	v_cvt_pk_bf16_f32 v26, v102, v103
	v_cvt_pk_bf16_f32 v27, v104, v105
	ds_write_b64 v4, v[38:39] offset:64
	ds_write_b64 v4, v[26:27] offset:8512
	ds_read_b128 v[26:29], v2 offset:43200
	s_waitcnt lgkmcnt(0)
	v_pk_mul_f32 v[32:33], v[132:133], v[28:29]
	v_pk_mul_f32 v[30:31], v[130:131], v[26:27]
	v_pk_mul_f32 v[28:29], v[100:101], v[28:29]
	v_pk_mul_f32 v[26:27], v[98:99], v[26:27]
	s_waitcnt vmcnt(26)
	v_mfma_f32_16x16x32_bf16 v[30:33], v[18:21], v[172:175], v[30:33]
	v_mfma_f32_16x16x32_bf16 v[18:21], v[18:21], v[180:183], v[26:29]
	s_waitcnt vmcnt(25)
	v_mfma_f32_16x16x32_bf16 v[130:133], v[22:25], v[176:179], v[30:33]
	v_mfma_f32_16x16x32_bf16 v[98:101], v[22:25], v[184:187], v[18:21]
	s_nop 6
	v_cvt_pk_bf16_f32 v26, v130, v131
	v_cvt_pk_bf16_f32 v27, v132, v133
	v_cvt_pk_bf16_f32 v18, v98, v99
	v_cvt_pk_bf16_f32 v19, v100, v101
	ds_write_b64 v4, v[26:27] offset:96
	ds_write_b64 v4, v[18:19] offset:8544
	s_cbranch_vccnz .LBB0_256
	v_add_u32_e32 v18, s75, v204
	s_waitcnt vmcnt(13)
	ds_write_b128 v18, v[58:61] offset:43008
.LBB0_256:
	s_min_u32 s97, s74, 0x7c
	s_add_i32 s97, s97, 3
	s_lshl_b32 s26, s97, 6
	s_add_i32 s26, s26, s94
	v_mad_i64_i32 v[18:19], s[26:27], s26, v230, v[146:147]
	v_add_co_u32_e32 v20, vcc, 0xc000, v18
	s_waitcnt lgkmcnt(0)
	s_barrier
	s_nop 0
	v_addc_co_u32_e32 v21, vcc, 0, v19, vcc
	global_load_dwordx4 v[50:53], v[18:19], off
	global_load_dwordx4 v[54:57], v[20:21], off offset:256
	v_add_co_u32_e32 v20, vcc, 0x18000, v18
	s_nop 1
	v_addc_co_u32_e32 v21, vcc, 0, v19, vcc
	v_add_co_u32_e32 v22, vcc, 0x24000, v18
	s_nop 1
	v_addc_co_u32_e32 v23, vcc, 0, v19, vcc
	global_load_dwordx4 v[38:41], v[20:21], off offset:512
	global_load_dwordx4 v[42:45], v[22:23], off offset:768
	v_add_co_u32_e32 v20, vcc, 0x30000, v18
	s_nop 1
	v_addc_co_u32_e32 v21, vcc, 0, v19, vcc
	v_add_co_u32_e32 v22, vcc, 0x3c000, v18
	s_nop 1
	v_addc_co_u32_e32 v23, vcc, 0, v19, vcc
	global_load_dwordx4 v[26:29], v[20:21], off offset:1024
	global_load_dwordx4 v[30:33], v[22:23], off offset:1280
	v_add_co_u32_e32 v20, vcc, 0x48000, v18
	s_nop 1
	v_addc_co_u32_e32 v21, vcc, 0, v19, vcc
	v_add_co_u32_e32 v22, vcc, 0x54000, v18
	s_nop 1
	v_addc_co_u32_e32 v23, vcc, 0, v19, vcc
	global_load_dwordx4 v[18:21], v[20:21], off offset:1536
	s_nop 0
	global_load_dwordx4 v[22:25], v[22:23], off offset:1792
	s_and_b64 vcc, exec, s[16:17]
	s_lshl_b32 s26, s97, 2
	s_add_i32 s26, s26, s22
	s_ashr_i32 s27, s26, 31
	s_lshl_b64 s[26:27], s[26:27], 10
	v_lshl_add_u64 v[6:7], v[158:159], 0, s[26:27]
	global_load_dwordx4 v[6:9], v[6:7], off
	s_min_u32 s99, s74, 0x7c
	s_add_i32 s99, s99, 5
	s_min_u32 s99, s99, 0x7f
	v_mad_u64_u32 v[240:241], vcc, v238, s99, v[236:237]
	global_load_dword v239, v[240:241], off
	s_lshl_b32 s99, s99, 6
	s_add_i32 s99, s99, s94
	s_mul_hi_u32 s101, s99, 0x6080
	s_mul_i32 s100, s99, 0x6080
	s_add_u32 s100, s100, s56
	s_addc_u32 s101, s101, s57
	global_load_dword v239, v242, s[100:101]
.LBB0_258:
	v_add_u32_e32 v167, s75, v166
	s_mulk_i32 s96, 0x1200
	ds_read_b128 v[168:171], v167 offset:43008
	v_add3_u32 v184, v206, s96, v208
	ds_read_b128 v[172:175], v184 offset:33792
	ds_read_b128 v[176:179], v184 offset:33856
	ds_read_b128 v[180:183], v184 offset:36096
	ds_read_b128 v[184:187], v184 offset:36160
	s_mulk_i32 s95, 0x4200
	s_waitcnt lgkmcnt(4)
	v_pk_mul_f32 v[116:117], v[116:117], v[170:171]
	v_pk_mul_f32 v[114:115], v[114:115], v[168:169]
	v_pk_mul_f32 v[112:113], v[112:113], v[170:171]
	v_pk_mul_f32 v[110:111], v[110:111], v[168:169]
	s_waitcnt vmcnt(32) lgkmcnt(3)
	v_mfma_f32_16x16x32_bf16 v[114:117], v[10:13], v[172:175], v[114:117]
	v_add3_u32 v231, v165, s95, v209
	s_and_b64 vcc, exec, s[16:17]
	s_waitcnt lgkmcnt(1)
	v_mfma_f32_16x16x32_bf16 v[110:113], v[10:13], v[180:183], v[110:113]
	s_waitcnt vmcnt(31)
	v_mfma_f32_16x16x32_bf16 v[114:117], v[14:17], v[176:179], v[114:117]
	s_waitcnt lgkmcnt(0)
	v_mfma_f32_16x16x32_bf16 v[110:113], v[14:17], v[184:187], v[110:113]
	s_nop 5
	v_cvt_pk_bf16_f32 v168, v114, v115
	v_cvt_pk_bf16_f32 v169, v116, v117
	ds_write_b64 v231, v[168:169]
	v_cvt_pk_bf16_f32 v168, v110, v111
	v_cvt_pk_bf16_f32 v169, v112, v113
	ds_write_b64 v231, v[168:169] offset:8448
	ds_read_b128 v[168:171], v167 offset:43072
	s_waitcnt lgkmcnt(0)
	v_pk_mul_f32 v[120:121], v[120:121], v[170:171]
	v_pk_mul_f32 v[118:119], v[118:119], v[168:169]
	v_pk_mul_f32 v[108:109], v[108:109], v[170:171]
	v_pk_mul_f32 v[106:107], v[106:107], v[168:169]
	s_waitcnt vmcnt(30)
	v_mfma_f32_16x16x32_bf16 v[118:121], v[34:37], v[172:175], v[118:121]
	v_mfma_f32_16x16x32_bf16 v[106:109], v[34:37], v[180:183], v[106:109]
	s_waitcnt vmcnt(29)
	v_mfma_f32_16x16x32_bf16 v[118:121], v[46:49], v[176:179], v[118:121]
	v_mfma_f32_16x16x32_bf16 v[106:109], v[46:49], v[184:187], v[106:109]
	s_nop 6
	v_cvt_pk_bf16_f32 v168, v118, v119
	v_cvt_pk_bf16_f32 v169, v120, v121
	ds_write_b64 v231, v[168:169] offset:32
	v_cvt_pk_bf16_f32 v168, v106, v107
	v_cvt_pk_bf16_f32 v169, v108, v109
	ds_write_b64 v231, v[168:169] offset:8480
	ds_read_b128 v[168:171], v167 offset:43136
	s_waitcnt lgkmcnt(0)
	v_pk_mul_f32 v[136:137], v[136:137], v[170:171]
	v_pk_mul_f32 v[134:135], v[134:135], v[168:169]
	v_pk_mul_f32 v[104:105], v[104:105], v[170:171]
	v_pk_mul_f32 v[102:103], v[102:103], v[168:169]
	s_waitcnt vmcnt(28)
	v_mfma_f32_16x16x32_bf16 v[134:137], v[62:65], v[172:175], v[134:137]
	v_mfma_f32_16x16x32_bf16 v[102:105], v[62:65], v[180:183], v[102:105]
	s_waitcnt vmcnt(27)
	v_mfma_f32_16x16x32_bf16 v[134:137], v[66:69], v[176:179], v[134:137]
	v_mfma_f32_16x16x32_bf16 v[102:105], v[66:69], v[184:187], v[102:105]
	s_nop 6
	v_cvt_pk_bf16_f32 v168, v134, v135
	v_cvt_pk_bf16_f32 v169, v136, v137
	ds_write_b64 v231, v[168:169] offset:64
	v_cvt_pk_bf16_f32 v168, v102, v103
	v_cvt_pk_bf16_f32 v169, v104, v105
	ds_write_b64 v231, v[168:169] offset:8512
	ds_read_b128 v[168:171], v167 offset:43200
	s_waitcnt lgkmcnt(0)
	v_pk_mul_f32 v[132:133], v[132:133], v[170:171]
	v_pk_mul_f32 v[130:131], v[130:131], v[168:169]
	v_pk_mul_f32 v[100:101], v[100:101], v[170:171]
	v_pk_mul_f32 v[98:99], v[98:99], v[168:169]
	s_waitcnt vmcnt(26)
	v_mfma_f32_16x16x32_bf16 v[130:133], v[70:73], v[172:175], v[130:133]
	v_mfma_f32_16x16x32_bf16 v[98:101], v[70:73], v[180:183], v[98:101]
	s_waitcnt vmcnt(25)
	v_mfma_f32_16x16x32_bf16 v[130:133], v[74:77], v[176:179], v[130:133]
	v_mfma_f32_16x16x32_bf16 v[98:101], v[74:77], v[184:187], v[98:101]
	s_nop 6
	v_cvt_pk_bf16_f32 v168, v130, v131
	v_cvt_pk_bf16_f32 v169, v132, v133
	ds_write_b64 v231, v[168:169] offset:96
	v_cvt_pk_bf16_f32 v168, v98, v99
	v_cvt_pk_bf16_f32 v169, v100, v101
	ds_write_b64 v231, v[168:169] offset:8544
	s_cbranch_vccnz .LBB0_260
	v_lshl_add_u32 v167, v202, 2, s86
	s_waitcnt vmcnt(13)
	ds_write_b128 v167, v[78:81] offset:43008
.LBB0_260:
	s_cmpk_gt_u32 s74, 0x7d
	s_cbranch_scc1 .LBB0_251
	s_min_u32 s86, s74, 0x7b
	s_add_i32 s86, s86, 4
	s_lshl_b32 s26, s86, 6
	s_add_i32 s26, s26, s94
	v_mad_i64_i32 v[70:71], s[26:27], s26, v230, v[146:147]
	v_add_co_u32_e32 v14, vcc, 0xc000, v70
	s_waitcnt lgkmcnt(0)
	s_barrier
	s_nop 0
	v_addc_co_u32_e32 v15, vcc, 0, v71, vcc
	v_add_co_u32_e32 v34, vcc, 0x18000, v70
	global_load_dwordx4 v[10:13], v[70:71], off
	s_nop 0
	global_load_dwordx4 v[14:17], v[14:15], off offset:256
	v_addc_co_u32_e32 v35, vcc, 0, v71, vcc
	v_add_co_u32_e32 v46, vcc, 0x24000, v70
	s_nop 1
	v_addc_co_u32_e32 v47, vcc, 0, v71, vcc
	v_add_co_u32_e32 v62, vcc, 0x30000, v70
	global_load_dwordx4 v[34:37], v[34:35], off offset:512
	s_nop 0
	global_load_dwordx4 v[46:49], v[46:47], off offset:768
	v_addc_co_u32_e32 v63, vcc, 0, v71, vcc
	v_add_co_u32_e32 v66, vcc, 0x3c000, v70
	s_nop 1
	v_addc_co_u32_e32 v67, vcc, 0, v71, vcc
	v_add_co_u32_e32 v72, vcc, 0x48000, v70
	global_load_dwordx4 v[62:65], v[62:63], off offset:1024
	s_nop 0
	global_load_dwordx4 v[66:69], v[66:67], off offset:1280
	v_addc_co_u32_e32 v73, vcc, 0, v71, vcc
	v_add_co_u32_e32 v74, vcc, 0x54000, v70
	s_nop 1
	v_addc_co_u32_e32 v75, vcc, 0, v71, vcc
	global_load_dwordx4 v[70:73], v[72:73], off offset:1536
	s_nop 0
	global_load_dwordx4 v[74:77], v[74:75], off offset:1792
	s_and_b64 vcc, exec, s[16:17]
	s_lshl_b32 s26, s86, 2
	s_add_i32 s26, s26, s22
	s_ashr_i32 s27, s26, 31
	s_lshl_b64 s[26:27], s[26:27], 10
	v_lshl_add_u64 v[58:59], v[158:159], 0, s[26:27]
	global_load_dwordx4 v[58:61], v[58:59], off
	s_min_u32 s99, s74, 0x7b
	s_add_i32 s99, s99, 6
	s_min_u32 s99, s99, 0x7f
	v_mad_u64_u32 v[240:241], vcc, v238, s99, v[236:237]
	global_load_dword v239, v[240:241], off
	s_lshl_b32 s99, s99, 6
	s_add_i32 s99, s99, s94
	s_mul_hi_u32 s101, s99, 0x6080
	s_mul_i32 s100, s99, 0x6080
	s_add_u32 s100, s100, s56
	s_addc_u32 s101, s101, s57
	global_load_dword v239, v242, s[100:101]
.LBB0_263:
	ds_read_b128 v[168:171], v2 offset:43008
	ds_read_b128 v[172:175], v5 offset:33792
	ds_read_b128 v[176:179], v5 offset:33856
	ds_read_b128 v[180:183], v5 offset:36096
	s_and_b64 vcc, exec, s[16:17]
	s_waitcnt lgkmcnt(3)
	v_pk_mul_f32 v[116:117], v[116:117], v[170:171]
	v_pk_mul_f32 v[114:115], v[114:115], v[168:169]
	v_pk_mul_f32 v[112:113], v[112:113], v[170:171]
	v_pk_mul_f32 v[110:111], v[110:111], v[168:169]
	s_waitcnt vmcnt(32) lgkmcnt(2)
	v_mfma_f32_16x16x32_bf16 v[114:117], v[142:145], v[172:175], v[114:117]
	s_waitcnt lgkmcnt(0)
	v_mfma_f32_16x16x32_bf16 v[110:113], v[142:145], v[180:183], v[110:113]
	ds_read_b128 v[142:145], v5 offset:36160
	s_waitcnt vmcnt(31)
	v_mfma_f32_16x16x32_bf16 v[114:117], v[138:141], v[176:179], v[114:117]
	s_waitcnt lgkmcnt(0)
	v_mfma_f32_16x16x32_bf16 v[110:113], v[138:141], v[142:145], v[110:113]
	s_nop 5
	v_cvt_pk_bf16_f32 v168, v114, v115
	v_cvt_pk_bf16_f32 v169, v116, v117
	v_cvt_pk_bf16_f32 v138, v110, v111
	v_cvt_pk_bf16_f32 v139, v112, v113
	ds_write_b64 v4, v[168:169]
	ds_write_b64 v4, v[138:139] offset:8448
	ds_read_b128 v[138:141], v2 offset:43072
	s_waitcnt lgkmcnt(0)
	v_pk_mul_f32 v[120:121], v[120:121], v[140:141]
	v_pk_mul_f32 v[118:119], v[118:119], v[138:139]
	v_pk_mul_f32 v[108:109], v[108:109], v[140:141]
	v_pk_mul_f32 v[106:107], v[106:107], v[138:139]
	s_waitcnt vmcnt(30)
	v_mfma_f32_16x16x32_bf16 v[118:121], v[126:129], v[172:175], v[118:121]
	v_mfma_f32_16x16x32_bf16 v[106:109], v[126:129], v[180:183], v[106:109]
	s_waitcnt vmcnt(29)
	v_mfma_f32_16x16x32_bf16 v[118:121], v[122:125], v[176:179], v[118:121]
	v_mfma_f32_16x16x32_bf16 v[106:109], v[122:125], v[142:145], v[106:109]
	s_nop 6
	v_cvt_pk_bf16_f32 v126, v118, v119
	v_cvt_pk_bf16_f32 v127, v120, v121
	v_cvt_pk_bf16_f32 v122, v106, v107
	v_cvt_pk_bf16_f32 v123, v108, v109
	ds_write_b64 v4, v[126:127] offset:32
	ds_write_b64 v4, v[122:123] offset:8480
	ds_read_b128 v[122:125], v2 offset:43136
	s_waitcnt lgkmcnt(0)
	v_pk_mul_f32 v[128:129], v[136:137], v[124:125]
	v_pk_mul_f32 v[126:127], v[134:135], v[122:123]
	v_pk_mul_f32 v[104:105], v[104:105], v[124:125]
	v_pk_mul_f32 v[102:103], v[102:103], v[122:123]
	s_waitcnt vmcnt(28)
	v_mfma_f32_16x16x32_bf16 v[126:129], v[94:97], v[172:175], v[126:129]
	v_mfma_f32_16x16x32_bf16 v[94:97], v[94:97], v[180:183], v[102:105]
	s_waitcnt vmcnt(27)
	v_mfma_f32_16x16x32_bf16 v[134:137], v[90:93], v[176:179], v[126:129]
	v_mfma_f32_16x16x32_bf16 v[102:105], v[90:93], v[142:145], v[94:97]
	s_nop 6
	v_cvt_pk_bf16_f32 v122, v134, v135
	v_cvt_pk_bf16_f32 v123, v136, v137
	v_cvt_pk_bf16_f32 v90, v102, v103
	v_cvt_pk_bf16_f32 v91, v104, v105
	ds_write_b64 v4, v[122:123] offset:64
	ds_write_b64 v4, v[90:91] offset:8512
	ds_read_b128 v[90:93], v2 offset:43200
	s_waitcnt lgkmcnt(0)
	v_pk_mul_f32 v[96:97], v[132:133], v[92:93]
	v_pk_mul_f32 v[94:95], v[130:131], v[90:91]
	v_pk_mul_f32 v[92:93], v[100:101], v[92:93]
	v_pk_mul_f32 v[90:91], v[98:99], v[90:91]
	s_waitcnt vmcnt(26)
	v_mfma_f32_16x16x32_bf16 v[94:97], v[86:89], v[172:175], v[94:97]
	v_mfma_f32_16x16x32_bf16 v[86:89], v[86:89], v[180:183], v[90:93]
	s_waitcnt vmcnt(25)
	v_mfma_f32_16x16x32_bf16 v[130:133], v[82:85], v[176:179], v[94:97]
	v_mfma_f32_16x16x32_bf16 v[98:101], v[82:85], v[142:145], v[86:89]
	s_nop 6
	v_cvt_pk_bf16_f32 v90, v130, v131
	v_cvt_pk_bf16_f32 v91, v132, v133
	v_cvt_pk_bf16_f32 v82, v98, v99
	v_cvt_pk_bf16_f32 v83, v100, v101
	ds_write_b64 v4, v[90:91] offset:96
	ds_write_b64 v4, v[82:83] offset:8544
	s_cbranch_vccnz .LBB0_251
	v_add_u32_e32 v2, s75, v204
	s_waitcnt vmcnt(13)
	ds_write_b128 v2, v[6:9] offset:43008
	s_branch .LBB0_251

.Lpf_even_p9:
	s_and_b64 vcc, exec, s[6:7]
	s_cbranch_vccz .Lpf_isdw_p9
	v_readfirstlane_b32 s98, v202
	v_readfirstlane_b32 s99, v203
	v_readfirstlane_b32 s100, v204
	s_nop 3
	v_mov_b32_e32 v202, s98
	v_mov_b32_e32 v203, s99
	v_mov_b32_e32 v204, s100
	v_mov_b32_e32 v208, 0

.LBB0_694:
	s_min_u32 s39, s38, 0x7d
	s_add_i32 s39, s39, 2
	s_lshl_b32 s40, s39, 6
	s_add_i32 s40, s40, s37
	v_mad_i64_i32 v[2:3], s[40:41], s40, v194, v[144:145]
	s_waitcnt vmcnt(22)
	v_add_co_u32_e32 v80, vcc, s18, v2
	s_waitcnt lgkmcnt(0)
	s_barrier
	s_nop 0
	v_addc_co_u32_e32 v81, vcc, 0, v3, vcc
	global_load_dwordx4 v[140:143], v[2:3], off
	global_load_dwordx4 v[136:139], v[80:81], off offset:256
	v_add_co_u32_e32 v80, vcc, s19, v2
	s_nop 1
	v_addc_co_u32_e32 v81, vcc, 0, v3, vcc
	v_add_co_u32_e32 v82, vcc, s20, v2
	s_nop 1
	v_addc_co_u32_e32 v83, vcc, 0, v3, vcc
	global_load_dwordx4 v[124:127], v[80:81], off offset:512
	global_load_dwordx4 v[120:123], v[82:83], off offset:768
	v_add_co_u32_e32 v80, vcc, s21, v2
	s_nop 1
	v_addc_co_u32_e32 v81, vcc, 0, v3, vcc
	v_add_co_u32_e32 v82, vcc, 0x3c000, v2
	s_nop 1
	v_addc_co_u32_e32 v83, vcc, 0, v3, vcc
	global_load_dwordx4 v[96:99], v[80:81], off offset:1024
	global_load_dwordx4 v[88:91], v[82:83], off offset:1280
	v_add_co_u32_e32 v80, vcc, 0x48000, v2
	s_nop 1
	v_addc_co_u32_e32 v81, vcc, 0, v3, vcc
	v_add_co_u32_e32 v2, vcc, 0x54000, v2
	s_nop 1
	v_addc_co_u32_e32 v3, vcc, 0, v3, vcc
	global_load_dwordx4 v[84:87], v[80:81], off offset:1536
	s_nop 0
	global_load_dwordx4 v[80:83], v[2:3], off offset:1792
	s_and_b64 vcc, exec, s[6:7]
	s_lshl_b32 s39, s39, 3
	s_add_i32 s40, s39, s10
	s_ashr_i32 s41, s40, 31
	s_lshl_b64 s[40:41], s[40:41], 10
	v_lshl_add_u64 v[2:3], v[146:147], 0, s[40:41]
	global_load_dwordx4 v[76:79], v[2:3], off
	s_min_u32 s99, s38, 0x7d
	s_add_i32 s99, s99, 4
	s_min_u32 s99, s99, 0x7f
	v_mad_u64_u32 v[206:207], vcc, v204, s99, v[202:203]
	global_load_dword v205, v[206:207], off
	s_lshl_b32 s99, s99, 6
	s_add_i32 s99, s99, s37
	s_mul_hi_u32 s101, s99, 0x6080
	s_mul_i32 s100, s99, 0x6080
	s_add_u32 s100, s100, s56
	s_addc_u32 s101, s101, s57
	global_load_dword v205, v208, s[100:101]
.LBB0_696:
	s_and_b32 s41, s38, 1
	s_lshl_b32 s40, s41, 10
	s_mul_i32 s39, s41, 0x1200
	s_add_i32 s40, s40, 0
	v_add_u32_e32 v0, s39, v178
	s_add_i32 s39, s11, s40
	v_add_u32_e32 v3, v0, v180
	v_lshl_add_u32 v0, v177, 2, s39
	ds_read_b128 v[152:155], v0 offset:43008
	ds_read_b128 v[156:159], v3 offset:33792
	ds_read_b128 v[160:163], v3 offset:33856
	ds_read_b128 v[164:167], v3 offset:36096
	ds_read_b128 v[196:199], v3 offset:36160
	s_xor_b32 s42, s41, 1
	s_waitcnt lgkmcnt(4)
	v_pk_mul_f32 v[110:111], v[110:111], v[154:155]
	v_pk_mul_f32 v[108:109], v[108:109], v[152:153]
	v_pk_mul_f32 v[114:115], v[114:115], v[154:155]
	v_pk_mul_f32 v[112:113], v[112:113], v[152:153]
	s_waitcnt vmcnt(32) lgkmcnt(3)
	v_mfma_f32_16x16x32_bf16 v[108:111], v[48:51], v[156:159], v[108:111]
	s_mul_i32 s39, s42, 0x4200
	v_add_u32_e32 v2, s39, v149
	v_add_u32_e32 v2, v2, v181
	s_waitcnt lgkmcnt(1)
	v_mfma_f32_16x16x32_bf16 v[48:51], v[48:51], v[164:167], v[112:115]
	s_and_b64 vcc, exec, s[6:7]
	s_lshl_b32 s39, s42, 10
	s_waitcnt vmcnt(31)
	v_mfma_f32_16x16x32_bf16 v[108:111], v[52:55], v[160:163], v[108:111]
	s_waitcnt lgkmcnt(0)
	v_mfma_f32_16x16x32_bf16 v[112:115], v[52:55], v[196:199], v[48:51]
	s_nop 5
	v_cvt_pk_bf16_f32 v168, v108, v109
	v_cvt_pk_bf16_f32 v169, v110, v111
	v_cvt_pk_bf16_f32 v48, v112, v113
	v_cvt_pk_bf16_f32 v49, v114, v115
	ds_write_b64 v2, v[168:169]
	ds_write_b64 v2, v[48:49] offset:8448
	ds_read_b128 v[48:51], v0 offset:43072
	s_waitcnt lgkmcnt(0)
	v_pk_mul_f32 v[54:55], v[118:119], v[50:51]
	v_pk_mul_f32 v[52:53], v[116:117], v[48:49]
	v_pk_mul_f32 v[50:51], v[106:107], v[50:51]
	v_pk_mul_f32 v[48:49], v[104:105], v[48:49]
	s_waitcnt vmcnt(30)
	v_mfma_f32_16x16x32_bf16 v[52:55], v[40:43], v[156:159], v[52:55]
	v_mfma_f32_16x16x32_bf16 v[40:43], v[40:43], v[164:167], v[48:51]
	s_waitcnt vmcnt(29)
	v_mfma_f32_16x16x32_bf16 v[116:119], v[44:47], v[160:163], v[52:55]
	v_mfma_f32_16x16x32_bf16 v[104:107], v[44:47], v[196:199], v[40:43]
	s_nop 6
	v_cvt_pk_bf16_f32 v48, v116, v117
	v_cvt_pk_bf16_f32 v49, v118, v119
	v_cvt_pk_bf16_f32 v40, v104, v105
	v_cvt_pk_bf16_f32 v41, v106, v107
	ds_write_b64 v2, v[48:49] offset:32
	ds_write_b64 v2, v[40:41] offset:8480
	ds_read_b128 v[40:43], v0 offset:43136
	s_waitcnt lgkmcnt(0)
	v_pk_mul_f32 v[46:47], v[134:135], v[42:43]
	v_pk_mul_f32 v[44:45], v[132:133], v[40:41]
	v_pk_mul_f32 v[42:43], v[102:103], v[42:43]
	v_pk_mul_f32 v[40:41], v[100:101], v[40:41]
	s_waitcnt vmcnt(28)
	v_mfma_f32_16x16x32_bf16 v[44:47], v[28:31], v[156:159], v[44:47]
	v_mfma_f32_16x16x32_bf16 v[28:31], v[28:31], v[164:167], v[40:43]
	s_waitcnt vmcnt(27)
	v_mfma_f32_16x16x32_bf16 v[132:135], v[32:35], v[160:163], v[44:47]
	v_mfma_f32_16x16x32_bf16 v[100:103], v[32:35], v[196:199], v[28:31]
	s_nop 6
	v_cvt_pk_bf16_f32 v40, v132, v133
	v_cvt_pk_bf16_f32 v41, v134, v135
	v_cvt_pk_bf16_f32 v28, v100, v101
	v_cvt_pk_bf16_f32 v29, v102, v103
	ds_write_b64 v2, v[40:41] offset:64
	ds_write_b64 v2, v[28:29] offset:8512
	ds_read_b128 v[28:31], v0 offset:43200
	s_waitcnt lgkmcnt(0)
	v_pk_mul_f32 v[34:35], v[130:131], v[30:31]
	v_pk_mul_f32 v[32:33], v[128:129], v[28:29]
	v_pk_mul_f32 v[30:31], v[94:95], v[30:31]
	v_pk_mul_f32 v[28:29], v[92:93], v[28:29]
	s_waitcnt vmcnt(26)
	v_mfma_f32_16x16x32_bf16 v[32:35], v[16:19], v[156:159], v[32:35]
	v_mfma_f32_16x16x32_bf16 v[16:19], v[16:19], v[164:167], v[28:31]
	s_waitcnt vmcnt(25)
	v_mfma_f32_16x16x32_bf16 v[128:131], v[20:23], v[160:163], v[32:35]
	v_mfma_f32_16x16x32_bf16 v[92:95], v[20:23], v[196:199], v[16:19]
	s_nop 6
	v_cvt_pk_bf16_f32 v28, v128, v129
	v_cvt_pk_bf16_f32 v29, v130, v131
	v_cvt_pk_bf16_f32 v16, v92, v93
	v_cvt_pk_bf16_f32 v17, v94, v95
	ds_write_b64 v2, v[28:29] offset:96
	ds_write_b64 v2, v[16:17] offset:8544
	s_cbranch_vccnz .LBB0_698
	v_add_u32_e32 v16, s39, v176
	s_waitcnt vmcnt(13)
	ds_write_b128 v16, v[60:63] offset:43008
.LBB0_698:
	s_min_u32 s43, s38, 0x7c
	s_add_i32 s43, s43, 3
	s_lshl_b32 s44, s43, 6
	s_add_i32 s44, s44, s37
	v_mad_i64_i32 v[16:17], s[44:45], s44, v194, v[144:145]
	v_add_co_u32_e32 v18, vcc, 0xc000, v16
	s_waitcnt lgkmcnt(0)
	s_barrier
	s_nop 0
	v_addc_co_u32_e32 v19, vcc, 0, v17, vcc
	global_load_dwordx4 v[48:51], v[16:17], off
	global_load_dwordx4 v[52:55], v[18:19], off offset:256
	v_add_co_u32_e32 v18, vcc, 0x18000, v16
	s_nop 1
	v_addc_co_u32_e32 v19, vcc, 0, v17, vcc
	v_add_co_u32_e32 v20, vcc, 0x24000, v16
	s_nop 1
	v_addc_co_u32_e32 v21, vcc, 0, v17, vcc
	global_load_dwordx4 v[40:43], v[18:19], off offset:512
	global_load_dwordx4 v[44:47], v[20:21], off offset:768
	v_add_co_u32_e32 v18, vcc, 0x30000, v16
	s_nop 1
	v_addc_co_u32_e32 v19, vcc, 0, v17, vcc
	v_add_co_u32_e32 v20, vcc, 0x3c000, v16
	s_nop 1
	v_addc_co_u32_e32 v21, vcc, 0, v17, vcc
	global_load_dwordx4 v[28:31], v[18:19], off offset:1024
	global_load_dwordx4 v[32:35], v[20:21], off offset:1280
	v_add_co_u32_e32 v18, vcc, 0x48000, v16
	s_nop 1
	v_addc_co_u32_e32 v19, vcc, 0, v17, vcc
	v_add_co_u32_e32 v20, vcc, 0x54000, v16
	s_nop 1
	v_addc_co_u32_e32 v21, vcc, 0, v17, vcc
	global_load_dwordx4 v[16:19], v[18:19], off offset:1536
	s_nop 0
	global_load_dwordx4 v[20:23], v[20:21], off offset:1792
	s_and_b64 vcc, exec, s[6:7]
	s_lshl_b32 s43, s43, 3
	s_add_i32 s44, s43, s10
	s_ashr_i32 s45, s44, 31
	s_lshl_b64 s[44:45], s[44:45], 10
	v_lshl_add_u64 v[4:5], v[146:147], 0, s[44:45]
	global_load_dwordx4 v[4:7], v[4:5], off
	s_min_u32 s99, s38, 0x7c
	s_add_i32 s99, s99, 5
	s_min_u32 s99, s99, 0x7f
	v_mad_u64_u32 v[206:207], vcc, v204, s99, v[202:203]
	global_load_dword v205, v[206:207], off
	s_lshl_b32 s99, s99, 6
	s_add_i32 s99, s99, s37
	s_mul_hi_u32 s101, s99, 0x6080
	s_mul_i32 s100, s99, 0x6080
	s_add_u32 s100, s100, s56
	s_addc_u32 s101, s101, s57
	global_load_dword v205, v208, s[100:101]
.LBB0_700:
	v_add_u32_e32 v151, s39, v150
	s_mulk_i32 s42, 0x1200
	ds_read_b128 v[152:155], v151 offset:43008
	v_add3_u32 v168, v178, s42, v180
	ds_read_b128 v[156:159], v168 offset:33792
	ds_read_b128 v[160:163], v168 offset:33856
	ds_read_b128 v[164:167], v168 offset:36096
	ds_read_b128 v[196:199], v168 offset:36160
	s_mulk_i32 s41, 0x4200
	s_waitcnt lgkmcnt(4)
	v_pk_mul_f32 v[110:111], v[110:111], v[154:155]
	v_pk_mul_f32 v[108:109], v[108:109], v[152:153]
	v_pk_mul_f32 v[114:115], v[114:115], v[154:155]
	v_pk_mul_f32 v[112:113], v[112:113], v[152:153]
	s_waitcnt vmcnt(32) lgkmcnt(3)
	v_mfma_f32_16x16x32_bf16 v[108:111], v[8:11], v[156:159], v[108:111]
	v_add3_u32 v168, v149, s41, v181
	s_and_b64 vcc, exec, s[6:7]
	s_waitcnt lgkmcnt(1)
	v_mfma_f32_16x16x32_bf16 v[112:115], v[8:11], v[164:167], v[112:115]
	s_waitcnt vmcnt(31)
	v_mfma_f32_16x16x32_bf16 v[108:111], v[12:15], v[160:163], v[108:111]
	s_waitcnt lgkmcnt(0)
	v_mfma_f32_16x16x32_bf16 v[112:115], v[12:15], v[196:199], v[112:115]
	s_nop 5
	v_cvt_pk_bf16_f32 v152, v108, v109
	v_cvt_pk_bf16_f32 v153, v110, v111
	ds_write_b64 v168, v[152:153]
	v_cvt_pk_bf16_f32 v152, v112, v113
	v_cvt_pk_bf16_f32 v153, v114, v115
	ds_write_b64 v168, v[152:153] offset:8448
	ds_read_b128 v[152:155], v151 offset:43072
	s_waitcnt lgkmcnt(0)
	v_pk_mul_f32 v[118:119], v[118:119], v[154:155]
	v_pk_mul_f32 v[116:117], v[116:117], v[152:153]
	v_pk_mul_f32 v[106:107], v[106:107], v[154:155]
	v_pk_mul_f32 v[104:105], v[104:105], v[152:153]
	s_waitcnt vmcnt(30)
	v_mfma_f32_16x16x32_bf16 v[116:119], v[24:27], v[156:159], v[116:119]
	v_mfma_f32_16x16x32_bf16 v[104:107], v[24:27], v[164:167], v[104:107]
	s_waitcnt vmcnt(29)
	v_mfma_f32_16x16x32_bf16 v[116:119], v[36:39], v[160:163], v[116:119]
	v_mfma_f32_16x16x32_bf16 v[104:107], v[36:39], v[196:199], v[104:107]
	s_nop 6
	v_cvt_pk_bf16_f32 v152, v116, v117
	v_cvt_pk_bf16_f32 v153, v118, v119
	ds_write_b64 v168, v[152:153] offset:32
	v_cvt_pk_bf16_f32 v152, v104, v105
	v_cvt_pk_bf16_f32 v153, v106, v107
	ds_write_b64 v168, v[152:153] offset:8480
	ds_read_b128 v[152:155], v151 offset:43136
	s_waitcnt lgkmcnt(0)
	v_pk_mul_f32 v[134:135], v[134:135], v[154:155]
	v_pk_mul_f32 v[132:133], v[132:133], v[152:153]
	v_pk_mul_f32 v[102:103], v[102:103], v[154:155]
	v_pk_mul_f32 v[100:101], v[100:101], v[152:153]
	s_waitcnt vmcnt(28)
	v_mfma_f32_16x16x32_bf16 v[132:135], v[56:59], v[156:159], v[132:135]
	v_mfma_f32_16x16x32_bf16 v[100:103], v[56:59], v[164:167], v[100:103]
	s_waitcnt vmcnt(27)
	v_mfma_f32_16x16x32_bf16 v[132:135], v[64:67], v[160:163], v[132:135]
	v_mfma_f32_16x16x32_bf16 v[100:103], v[64:67], v[196:199], v[100:103]
	s_nop 6
	v_cvt_pk_bf16_f32 v152, v132, v133
	v_cvt_pk_bf16_f32 v153, v134, v135
	ds_write_b64 v168, v[152:153] offset:64
	v_cvt_pk_bf16_f32 v152, v100, v101
	v_cvt_pk_bf16_f32 v153, v102, v103
	ds_write_b64 v168, v[152:153] offset:8512
	ds_read_b128 v[152:155], v151 offset:43200
	s_waitcnt lgkmcnt(0)
	v_pk_mul_f32 v[130:131], v[130:131], v[154:155]
	v_pk_mul_f32 v[128:129], v[128:129], v[152:153]
	v_pk_mul_f32 v[94:95], v[94:95], v[154:155]
	v_pk_mul_f32 v[92:93], v[92:93], v[152:153]
	s_waitcnt vmcnt(26)
	v_mfma_f32_16x16x32_bf16 v[128:131], v[68:71], v[156:159], v[128:131]
	v_mfma_f32_16x16x32_bf16 v[92:95], v[68:71], v[164:167], v[92:95]
	s_waitcnt vmcnt(25)
	v_mfma_f32_16x16x32_bf16 v[128:131], v[72:75], v[160:163], v[128:131]
	v_mfma_f32_16x16x32_bf16 v[92:95], v[72:75], v[196:199], v[92:95]
	s_nop 6
	v_cvt_pk_bf16_f32 v152, v128, v129
	v_cvt_pk_bf16_f32 v153, v130, v131
	ds_write_b64 v168, v[152:153] offset:96
	v_cvt_pk_bf16_f32 v152, v92, v93
	v_cvt_pk_bf16_f32 v153, v94, v95
	ds_write_b64 v168, v[152:153] offset:8544
	s_cbranch_vccnz .LBB0_702
	v_lshl_add_u32 v151, v174, 2, s40
	s_waitcnt vmcnt(13)
	ds_write_b128 v151, v[76:79] offset:43008
.LBB0_702:
	s_cmpk_gt_u32 s38, 0x7d
	s_cbranch_scc1 .LBB0_693
	s_min_u32 s40, s38, 0x7b
	s_add_i32 s40, s40, 4
	s_lshl_b32 s41, s40, 6
	s_add_i32 s41, s41, s37
	v_mad_i64_i32 v[68:69], s[42:43], s41, v194, v[144:145]
	v_add_co_u32_e32 v12, vcc, 0xc000, v68
	s_waitcnt lgkmcnt(0)
	s_barrier
	s_nop 0
	v_addc_co_u32_e32 v13, vcc, 0, v69, vcc
	v_add_co_u32_e32 v24, vcc, 0x18000, v68
	global_load_dwordx4 v[8:11], v[68:69], off
	s_nop 0
	global_load_dwordx4 v[12:15], v[12:13], off offset:256
	v_addc_co_u32_e32 v25, vcc, 0, v69, vcc
	v_add_co_u32_e32 v36, vcc, 0x24000, v68
	s_nop 1
	v_addc_co_u32_e32 v37, vcc, 0, v69, vcc
	v_add_co_u32_e32 v56, vcc, 0x30000, v68
	global_load_dwordx4 v[24:27], v[24:25], off offset:512
	s_nop 0
	global_load_dwordx4 v[36:39], v[36:37], off offset:768
	v_addc_co_u32_e32 v57, vcc, 0, v69, vcc
	v_add_co_u32_e32 v64, vcc, 0x3c000, v68
	s_nop 1
	v_addc_co_u32_e32 v65, vcc, 0, v69, vcc
	v_add_co_u32_e32 v70, vcc, 0x48000, v68
	global_load_dwordx4 v[56:59], v[56:57], off offset:1024
	s_nop 0
	global_load_dwordx4 v[64:67], v[64:65], off offset:1280
	v_addc_co_u32_e32 v71, vcc, 0, v69, vcc
	v_add_co_u32_e32 v72, vcc, 0x54000, v68
	s_nop 1
	v_addc_co_u32_e32 v73, vcc, 0, v69, vcc
	global_load_dwordx4 v[68:71], v[70:71], off offset:1536
	s_nop 0
	global_load_dwordx4 v[72:75], v[72:73], off offset:1792
	s_and_b64 vcc, exec, s[6:7]
	s_lshl_b32 s40, s40, 3
	s_add_i32 s40, s40, s10
	s_ashr_i32 s41, s40, 31
	s_lshl_b64 s[40:41], s[40:41], 10
	v_lshl_add_u64 v[60:61], v[146:147], 0, s[40:41]
	global_load_dwordx4 v[60:63], v[60:61], off
	s_min_u32 s99, s38, 0x7b
	s_add_i32 s99, s99, 6
	s_min_u32 s99, s99, 0x7f
	v_mad_u64_u32 v[206:207], vcc, v204, s99, v[202:203]
	global_load_dword v205, v[206:207], off
	s_lshl_b32 s99, s99, 6
	s_add_i32 s99, s99, s37
	s_mul_hi_u32 s101, s99, 0x6080
	s_mul_i32 s100, s99, 0x6080
	s_add_u32 s100, s100, s56
	s_addc_u32 s101, s101, s57
	global_load_dword v205, v208, s[100:101]
.LBB0_705:
	ds_read_b128 v[152:155], v0 offset:43008
	ds_read_b128 v[156:159], v3 offset:33792
	ds_read_b128 v[160:163], v3 offset:33856
	ds_read_b128 v[164:167], v3 offset:36096
	s_and_b64 vcc, exec, s[6:7]
	s_waitcnt lgkmcnt(3)
	v_pk_mul_f32 v[110:111], v[110:111], v[154:155]
	v_pk_mul_f32 v[108:109], v[108:109], v[152:153]
	v_pk_mul_f32 v[114:115], v[114:115], v[154:155]
	v_pk_mul_f32 v[112:113], v[112:113], v[152:153]
	s_waitcnt vmcnt(32) lgkmcnt(2)
	v_mfma_f32_16x16x32_bf16 v[108:111], v[140:143], v[156:159], v[108:111]
	s_waitcnt lgkmcnt(0)
	v_mfma_f32_16x16x32_bf16 v[112:115], v[140:143], v[164:167], v[112:115]
	ds_read_b128 v[140:143], v3 offset:36160
	s_waitcnt vmcnt(31)
	v_mfma_f32_16x16x32_bf16 v[108:111], v[136:139], v[160:163], v[108:111]
	s_waitcnt lgkmcnt(0)
	v_mfma_f32_16x16x32_bf16 v[112:115], v[136:139], v[140:143], v[112:115]
	s_nop 5
	v_cvt_pk_bf16_f32 v152, v108, v109
	v_cvt_pk_bf16_f32 v153, v110, v111
	v_cvt_pk_bf16_f32 v136, v112, v113
	v_cvt_pk_bf16_f32 v137, v114, v115
	ds_write_b64 v2, v[152:153]
	ds_write_b64 v2, v[136:137] offset:8448
	ds_read_b128 v[136:139], v0 offset:43072
	s_waitcnt lgkmcnt(0)
	v_pk_mul_f32 v[118:119], v[118:119], v[138:139]
	v_pk_mul_f32 v[116:117], v[116:117], v[136:137]
	v_pk_mul_f32 v[106:107], v[106:107], v[138:139]
	v_pk_mul_f32 v[104:105], v[104:105], v[136:137]
	s_waitcnt vmcnt(30)
	v_mfma_f32_16x16x32_bf16 v[116:119], v[124:127], v[156:159], v[116:119]
	v_mfma_f32_16x16x32_bf16 v[104:107], v[124:127], v[164:167], v[104:107]
	s_waitcnt vmcnt(29)
	v_mfma_f32_16x16x32_bf16 v[116:119], v[120:123], v[160:163], v[116:119]
	v_mfma_f32_16x16x32_bf16 v[104:107], v[120:123], v[140:143], v[104:107]
	s_nop 6
	v_cvt_pk_bf16_f32 v124, v116, v117
	v_cvt_pk_bf16_f32 v125, v118, v119
	v_cvt_pk_bf16_f32 v120, v104, v105
	v_cvt_pk_bf16_f32 v121, v106, v107
	ds_write_b64 v2, v[124:125] offset:32
	ds_write_b64 v2, v[120:121] offset:8480
	ds_read_b128 v[120:123], v0 offset:43136
	s_waitcnt lgkmcnt(0)
	v_pk_mul_f32 v[126:127], v[134:135], v[122:123]
	v_pk_mul_f32 v[124:125], v[132:133], v[120:121]
	v_pk_mul_f32 v[102:103], v[102:103], v[122:123]
	v_pk_mul_f32 v[100:101], v[100:101], v[120:121]
	s_waitcnt vmcnt(28)
	v_mfma_f32_16x16x32_bf16 v[124:127], v[96:99], v[156:159], v[124:127]
	v_mfma_f32_16x16x32_bf16 v[96:99], v[96:99], v[164:167], v[100:103]
	s_waitcnt vmcnt(27)
	v_mfma_f32_16x16x32_bf16 v[132:135], v[88:91], v[160:163], v[124:127]
	v_mfma_f32_16x16x32_bf16 v[100:103], v[88:91], v[140:143], v[96:99]
	s_nop 6
	v_cvt_pk_bf16_f32 v120, v132, v133
	v_cvt_pk_bf16_f32 v121, v134, v135
	v_cvt_pk_bf16_f32 v88, v100, v101
	v_cvt_pk_bf16_f32 v89, v102, v103
	ds_write_b64 v2, v[120:121] offset:64
	ds_write_b64 v2, v[88:89] offset:8512
	ds_read_b128 v[88:91], v0 offset:43200
	s_waitcnt lgkmcnt(0)
	v_pk_mul_f32 v[98:99], v[130:131], v[90:91]
	v_pk_mul_f32 v[96:97], v[128:129], v[88:89]
	v_pk_mul_f32 v[90:91], v[94:95], v[90:91]
	v_pk_mul_f32 v[88:89], v[92:93], v[88:89]
	s_waitcnt vmcnt(26)
	v_mfma_f32_16x16x32_bf16 v[96:99], v[84:87], v[156:159], v[96:99]
	v_mfma_f32_16x16x32_bf16 v[84:87], v[84:87], v[164:167], v[88:91]
	s_waitcnt vmcnt(25)
	v_mfma_f32_16x16x32_bf16 v[128:131], v[80:83], v[160:163], v[96:99]
	v_mfma_f32_16x16x32_bf16 v[92:95], v[80:83], v[140:143], v[84:87]
	s_nop 6
	v_cvt_pk_bf16_f32 v88, v128, v129
	v_cvt_pk_bf16_f32 v89, v130, v131
	v_cvt_pk_bf16_f32 v80, v92, v93
	v_cvt_pk_bf16_f32 v81, v94, v95
	ds_write_b64 v2, v[88:89] offset:96
	ds_write_b64 v2, v[80:81] offset:8544
	s_cbranch_vccnz .LBB0_693
	v_add_u32_e32 v0, s39, v176
	s_waitcnt vmcnt(13)
	ds_write_b128 v0, v[4:7] offset:43008
	s_branch .LBB0_693
